# GEMM K loops: the back-to-back s_setprio 0 / s_setprio 1 pair between the two 16-MFMA halves of a cluster deleted (12 sites)
# speedup vs baseline: 1.0078x; 1.0078x over previous
; #define PG8_STAGE(bufoff, gbase, voff) do { _Pragma("unroll") for (int _i = 0; _i < 2; ++_i) \
;         __builtin_amdgcn_global_load_lds((const unsigned*)((const char*)(gbase) + (voff)[_i]), (PG8_LAS unsigned*)(lds + (bufoff) + ldsw + _i * 8192), 16, 0, 0); } while (0)
; #define PG8_LDA(dst, b, h) do { _Pragma("unroll") for (int m = 0; m < 4; ++m) _Pragma("unroll") for (int k = 0; k < 2; ++k) dst[m][k] = *(const PG8_LAS bf16x8*)(lds + PG8_SA(b, h) + aoff + m * 2048 + k * 1024); } while (0)
; #define PG8_LDB(dst, b, h) do { _Pragma("unroll") for (int n = 0; n < 2; ++n) _Pragma("unroll") for (int k = 0; k < 2; ++k) dst[n][k] = *(const PG8_LAS bf16x8*)(lds + PG8_SB(b, h) + boff + n * 2048 + k * 1024); } while (0)
; #define PG8_MMA(ai, bj, At, Bt) do { __builtin_amdgcn_s_setprio(1); _Pragma("unroll") for (int m = 0; m < 4; ++m) _Pragma("unroll") for (int n = 0; n < 2; ++n) _Pragma("unroll") for (int k = 0; k < 2; ++k) \
;         acc[ai][bj][m][n] = __builtin_amdgcn_mfma_f32_16x16x32_bf16(Bt[n][k], At[m][k], acc[ai][bj][m][n], 0, 0, 0); __builtin_amdgcn_s_setprio(0); } while (0)
; #define PG8_WAIT_V(n) asm volatile("s_waitcnt vmcnt(" #n ")" ::: "memory")
; #define PG8_WAIT_L(n) asm volatile("s_waitcnt lgkmcnt(" #n ")" ::: "memory")
; #define PG8_BAR __builtin_amdgcn_s_barrier()
; #define PG8_SCHED __builtin_amdgcn_sched_barrier(0)
; template <class Epi, class Sched, bool ALIGN_EPI = false, bool SP2 = false>
; __device__ __forceinline__ void gemm_phase(PG8_LAS unsigned char* lds, const Gemm g, const Sched& S, const Epi& E) {
;     ...
;         for (int t = 0; t < nt; t += 2) {
;             const bool last = (t == nt - 2);
;             const char* a1 = cA + (size_t)(t + 1) * kstep;
;             const char* a2 = last ? nA : cA + (size_t)(t + 2) * kstep; const char* b2 = last ? nB : cB + (size_t)(t + 2) * kstep;
;             const char* a3 = a2 + kstep; const char* b3 = b2 + kstep;
;             if (last && has_next) S.a_ready(nxt);
;             if constexpr (SP2) {
;             PG8_LDB(B0, 0, 0); PG8_LDB(B1, 0, 1); PG8_SCHED; PG8_LDA(At, 0, 0); PG8_STAGE(PG8_SA(1, 1), a1 + hstep, voffA);
;             PG8_WAIT_V(8); PG8_WAIT_L(0); PG8_BAR; PG8_MMA(0, 0, At, B0); PG8_MMA(0, 1, At, B1); PG8_BAR; PG8_SCHED;
;             PG8_LDA(At, 0, 1); PG8_STAGE(PG8_SB(0, 0), b2, voffB); PG8_STAGE(PG8_SB(0, 1), b2 + hstep, voffB); PG8_STAGE(PG8_SA(0, 0), a2, voffA);
.LBB0_313:
	s_add_i32 s67, s34, 2
	s_add_u32 s68, s30, 0x80
	s_addc_u32 s35, s31, 0
	s_cmp_eq_u32 s56, s34
	s_cselect_b32 s35, s9, s35
	s_cselect_b32 s34, s8, s68
	v_add_u32_e32 v144, s74, v135
	s_cselect_b32 s69, s29, s66
	s_cselect_b32 s68, s28, s65
	s_add_i32 s80, 0, 0x14000
	ds_read_b128 v[148:151], v144
	ds_read_b128 v[152:155], v144 offset:1024
	ds_read_b128 v[156:159], v144 offset:2048
	ds_read_b128 v[160:163], v144 offset:3072
	v_add_u32_e32 v144, s80, v135
	ds_read_b128 v[164:167], v144
	ds_read_b128 v[198:201], v144 offset:1024
	ds_read_b128 v[202:205], v144 offset:2048
	ds_read_b128 v[206:209], v144 offset:3072
	v_lshl_add_u64 v[144:145], s[30:31], 0, v[140:141]
	s_add_i32 m0, s47, 0xc000
	ds_read_b128 v[210:213], v147
	ds_read_b128 v[214:217], v147 offset:1024
	ds_read_b128 v[218:221], v147 offset:2048
	ds_read_b128 v[222:225], v147 offset:3072
	ds_read_b128 v[226:229], v147 offset:4096
	ds_read_b128 v[230:233], v147 offset:5120
	ds_read_b128 v[234:237], v147 offset:6144
	ds_read_b128 v[238:241], v147 offset:7168
	global_load_lds_dwordx4 v[144:145], off
	v_lshl_add_u64 v[144:145], s[30:31], 0, v[142:143]
	s_add_i32 m0, s47, 0xe000
	s_nop 0
	global_load_lds_dwordx4 v[144:145], off
	s_waitcnt vmcnt(8)
	s_waitcnt lgkmcnt(0)
	s_barrier
	s_setprio 1
	s_waitcnt lgkmcnt(0)
	v_mfma_f32_16x16x32_bf16 v[128:131], v[148:151], v[210:213], v[128:131]
	v_mfma_f32_16x16x32_bf16 v[124:127], v[156:159], v[210:213], v[124:127]
	v_mfma_f32_16x16x32_bf16 v[120:123], v[148:151], v[218:221], v[120:123]
	v_mfma_f32_16x16x32_bf16 v[112:115], v[156:159], v[218:221], v[112:115]
	v_mfma_f32_16x16x32_bf16 v[104:107], v[148:151], v[226:229], v[104:107]
	v_mfma_f32_16x16x32_bf16 v[96:99], v[156:159], v[226:229], v[96:99]
	v_mfma_f32_16x16x32_bf16 v[88:91], v[148:151], v[234:237], v[88:91]
	v_mfma_f32_16x16x32_bf16 v[80:83], v[156:159], v[234:237], v[80:83]
	v_mfma_f32_16x16x32_bf16 v[128:131], v[152:155], v[214:217], v[128:131]
	v_mfma_f32_16x16x32_bf16 v[124:127], v[160:163], v[214:217], v[124:127]
	v_mfma_f32_16x16x32_bf16 v[120:123], v[152:155], v[222:225], v[120:123]
	v_mfma_f32_16x16x32_bf16 v[112:115], v[160:163], v[222:225], v[112:115]
	v_mfma_f32_16x16x32_bf16 v[104:107], v[152:155], v[230:233], v[104:107]
	v_mfma_f32_16x16x32_bf16 v[96:99], v[160:163], v[230:233], v[96:99]
	v_mfma_f32_16x16x32_bf16 v[88:91], v[152:155], v[238:241], v[88:91]
	v_mfma_f32_16x16x32_bf16 v[80:83], v[160:163], v[238:241], v[80:83]
	v_mfma_f32_16x16x32_bf16 v[116:119], v[164:167], v[210:213], v[116:119]
	v_mfma_f32_16x16x32_bf16 v[108:111], v[202:205], v[210:213], v[108:111]
	v_mfma_f32_16x16x32_bf16 v[100:103], v[164:167], v[218:221], v[100:103]
	v_mfma_f32_16x16x32_bf16 v[92:95], v[202:205], v[218:221], v[92:95]
	v_mfma_f32_16x16x32_bf16 v[84:87], v[164:167], v[226:229], v[84:87]
	v_mfma_f32_16x16x32_bf16 v[76:79], v[202:205], v[226:229], v[76:79]
	v_mfma_f32_16x16x32_bf16 v[72:75], v[164:167], v[234:237], v[72:75]
	v_mfma_f32_16x16x32_bf16 v[68:71], v[202:205], v[234:237], v[68:71]
	v_mfma_f32_16x16x32_bf16 v[116:119], v[198:201], v[214:217], v[116:119]
	v_mfma_f32_16x16x32_bf16 v[108:111], v[206:209], v[214:217], v[108:111]
	v_mfma_f32_16x16x32_bf16 v[100:103], v[198:201], v[222:225], v[100:103]
	v_mfma_f32_16x16x32_bf16 v[92:95], v[206:209], v[222:225], v[92:95]
	v_mfma_f32_16x16x32_bf16 v[84:87], v[198:201], v[230:233], v[84:87]
	v_mfma_f32_16x16x32_bf16 v[76:79], v[206:209], v[230:233], v[76:79]
	v_mfma_f32_16x16x32_bf16 v[72:75], v[198:201], v[238:241], v[72:75]
	v_mfma_f32_16x16x32_bf16 v[68:71], v[206:209], v[238:241], v[68:71]
	s_setprio 0
	s_barrier
	s_add_i32 s81, s74, s42
	v_lshl_add_u64 v[144:145], s[68:69], 0, v[2:3]
	s_mov_b32 m0, s81
	ds_read_b128 v[210:213], v147 offset:16384
	ds_read_b128 v[214:217], v147 offset:17408
	ds_read_b128 v[218:221], v147 offset:18432
	ds_read_b128 v[222:225], v147 offset:19456
	ds_read_b128 v[226:229], v147 offset:20480
	ds_read_b128 v[230:233], v147 offset:21504
	ds_read_b128 v[234:237], v147 offset:22528
	ds_read_b128 v[238:241], v147 offset:23552
	global_load_lds_dwordx4 v[144:145], off
	s_add_i32 m0, s81, 0x2000
	v_lshl_add_u64 v[242:243], s[68:69], 0, v[0:1]
	s_add_u32 s68, s68, s58
	s_addc_u32 s69, s69, 0
	s_add_i32 s80, s80, s42
	global_load_lds_dwordx4 v[242:243], off
	v_lshl_add_u64 v[248:249], s[68:69], 0, v[2:3]
	s_mov_b32 m0, s80
	v_lshl_add_u64 v[250:251], s[68:69], 0, v[0:1]
	global_load_lds_dwordx4 v[248:249], off
	s_add_i32 m0, s80, 0x2000
	v_lshl_add_u64 v[252:253], s[34:35], 0, v[138:139]
	global_load_lds_dwordx4 v[250:251], off
	s_mov_b32 m0, s47
	v_lshl_add_u64 v[194:195], s[34:35], 0, v[136:137]
	global_load_lds_dwordx4 v[252:253], off
	s_mov_b32 m0, s48
	s_nop 0
	global_load_lds_dwordx4 v[194:195], off
	s_waitcnt vmcnt(8)
	s_waitcnt lgkmcnt(0)
	s_barrier
; #define PG8_STAGE(bufoff, gbase, voff) do { _Pragma("unroll") for (int _i = 0; _i < 2; ++_i) \
;         __builtin_amdgcn_global_load_lds((const unsigned*)((const char*)(gbase) + (voff)[_i]), (PG8_LAS unsigned*)(lds + (bufoff) + ldsw + _i * 8192), 16, 0, 0); } while (0)
; #define PG8_LDA(dst, b, h) do { _Pragma("unroll") for (int m = 0; m < 4; ++m) _Pragma("unroll") for (int k = 0; k < 2; ++k) dst[m][k] = *(const PG8_LAS bf16x8*)(lds + PG8_SA(b, h) + aoff + m * 2048 + k * 1024); } while (0)
; #define PG8_LDB(dst, b, h) do { _Pragma("unroll") for (int n = 0; n < 2; ++n) _Pragma("unroll") for (int k = 0; k < 2; ++k) dst[n][k] = *(const PG8_LAS bf16x8*)(lds + PG8_SB(b, h) + boff + n * 2048 + k * 1024); } while (0)
; #define PG8_MMA(ai, bj, At, Bt) do { __builtin_amdgcn_s_setprio(1); _Pragma("unroll") for (int m = 0; m < 4; ++m) _Pragma("unroll") for (int n = 0; n < 2; ++n) _Pragma("unroll") for (int k = 0; k < 2; ++k) \
;         acc[ai][bj][m][n] = __builtin_amdgcn_mfma_f32_16x16x32_bf16(Bt[n][k], At[m][k], acc[ai][bj][m][n], 0, 0, 0); __builtin_amdgcn_s_setprio(0); } while (0)
; #define PG8_WAIT_V(n) asm volatile("s_waitcnt vmcnt(" #n ")" ::: "memory")
; #define PG8_WAIT_L(n) asm volatile("s_waitcnt lgkmcnt(" #n ")" ::: "memory")
; #define PG8_BAR __builtin_amdgcn_s_barrier()
; #define PG8_SCHED __builtin_amdgcn_sched_barrier(0)
; template <class Epi, class Sched, bool ALIGN_EPI = false, bool SP2 = false>
; __device__ __forceinline__ void gemm_phase(PG8_LAS unsigned char* lds, const Gemm g, const Sched& S, const Epi& E) {
;     ...
;             PG8_WAIT_V(8); PG8_WAIT_L(0); PG8_BAR; PG8_MMA(1, 0, At, B0); PG8_MMA(1, 1, At, B1); PG8_BAR; PG8_SCHED;
;             PG8_LDB(B0, 1, 0); PG8_LDB(B1, 1, 1); PG8_SCHED; PG8_LDA(At, 1, 0); PG8_STAGE(PG8_SA(0, 1), a2 + hstep, voffA);
;             PG8_WAIT_V(8); PG8_WAIT_L(0); PG8_BAR; PG8_MMA(0, 0, At, B0); PG8_MMA(0, 1, At, B1); PG8_BAR; PG8_SCHED;
	s_setprio 1
	s_waitcnt lgkmcnt(0)
	v_mfma_f32_16x16x32_bf16 v[64:67], v[148:151], v[210:213], v[64:67]
	v_mfma_f32_16x16x32_bf16 v[60:63], v[156:159], v[210:213], v[60:63]
	v_mfma_f32_16x16x32_bf16 v[56:59], v[148:151], v[218:221], v[56:59]
	v_mfma_f32_16x16x32_bf16 v[48:51], v[156:159], v[218:221], v[48:51]
	v_mfma_f32_16x16x32_bf16 v[40:43], v[148:151], v[226:229], v[40:43]
	v_mfma_f32_16x16x32_bf16 v[32:35], v[156:159], v[226:229], v[32:35]
	v_mfma_f32_16x16x32_bf16 v[24:27], v[148:151], v[234:237], v[24:27]
	v_mfma_f32_16x16x32_bf16 v[16:19], v[156:159], v[234:237], v[16:19]
	v_mfma_f32_16x16x32_bf16 v[64:67], v[152:155], v[214:217], v[64:67]
	v_mfma_f32_16x16x32_bf16 v[60:63], v[160:163], v[214:217], v[60:63]
	v_mfma_f32_16x16x32_bf16 v[56:59], v[152:155], v[222:225], v[56:59]
	v_mfma_f32_16x16x32_bf16 v[48:51], v[160:163], v[222:225], v[48:51]
	v_mfma_f32_16x16x32_bf16 v[40:43], v[152:155], v[230:233], v[40:43]
	v_mfma_f32_16x16x32_bf16 v[32:35], v[160:163], v[230:233], v[32:35]
	v_mfma_f32_16x16x32_bf16 v[24:27], v[152:155], v[238:241], v[24:27]
	v_mfma_f32_16x16x32_bf16 v[16:19], v[160:163], v[238:241], v[16:19]
	v_mfma_f32_16x16x32_bf16 v[52:55], v[164:167], v[210:213], v[52:55]
	v_mfma_f32_16x16x32_bf16 v[44:47], v[202:205], v[210:213], v[44:47]
	v_mfma_f32_16x16x32_bf16 v[36:39], v[164:167], v[218:221], v[36:39]
	v_mfma_f32_16x16x32_bf16 v[28:31], v[202:205], v[218:221], v[28:31]
	v_mfma_f32_16x16x32_bf16 v[20:23], v[164:167], v[226:229], v[20:23]
	v_mfma_f32_16x16x32_bf16 v[12:15], v[202:205], v[226:229], v[12:15]
	v_mfma_f32_16x16x32_bf16 v[8:11], v[164:167], v[234:237], v[8:11]
	v_mfma_f32_16x16x32_bf16 v[4:7], v[202:205], v[234:237], v[4:7]
	v_mfma_f32_16x16x32_bf16 v[52:55], v[198:201], v[214:217], v[52:55]
	v_mfma_f32_16x16x32_bf16 v[44:47], v[206:209], v[214:217], v[44:47]
	v_mfma_f32_16x16x32_bf16 v[36:39], v[198:201], v[222:225], v[36:39]
	v_mfma_f32_16x16x32_bf16 v[28:31], v[206:209], v[222:225], v[28:31]
	v_mfma_f32_16x16x32_bf16 v[20:23], v[198:201], v[230:233], v[20:23]
	v_mfma_f32_16x16x32_bf16 v[12:15], v[206:209], v[230:233], v[12:15]
	v_mfma_f32_16x16x32_bf16 v[8:11], v[198:201], v[238:241], v[8:11]
	v_mfma_f32_16x16x32_bf16 v[4:7], v[206:209], v[238:241], v[4:7]
	s_setprio 0
	s_barrier
	s_add_i32 s68, 0, 0x18000
	s_add_i32 s69, 0, 0x1c000
	v_add_u32_e32 v160, s68, v135
	v_add_u32_e32 v196, s69, v135
	ds_read_b128 v[148:151], v160
	ds_read_b128 v[152:155], v160 offset:1024
	ds_read_b128 v[156:159], v160 offset:2048
	ds_read_b128 v[160:163], v160 offset:3072
	ds_read_b128 v[164:167], v196
	ds_read_b128 v[198:201], v196 offset:1024
	ds_read_b128 v[202:205], v196 offset:2048
	ds_read_b128 v[206:209], v196 offset:3072
	s_add_u32 s34, s34, s58
	s_addc_u32 s35, s35, 0
	s_mov_b32 m0, s49
	v_lshl_add_u64 v[196:197], s[34:35], 0, v[138:139]
	ds_read_b128 v[210:213], v147 offset:32768
	ds_read_b128 v[214:217], v147 offset:33792
	ds_read_b128 v[218:221], v147 offset:34816
	ds_read_b128 v[222:225], v147 offset:35840
	ds_read_b128 v[226:229], v147 offset:36864
	ds_read_b128 v[230:233], v147 offset:37888
	ds_read_b128 v[234:237], v147 offset:38912
	ds_read_b128 v[238:241], v147 offset:39936
	global_load_lds_dwordx4 v[196:197], off
	v_lshl_add_u64 v[196:197], s[34:35], 0, v[136:137]
	s_mov_b32 m0, s50
	s_nop 0
	global_load_lds_dwordx4 v[196:197], off
	s_waitcnt vmcnt(8)
	s_waitcnt lgkmcnt(0)
	s_barrier
	s_setprio 1
	s_waitcnt lgkmcnt(0)
	v_mfma_f32_16x16x32_bf16 v[128:131], v[148:151], v[210:213], v[128:131]
	v_mfma_f32_16x16x32_bf16 v[124:127], v[156:159], v[210:213], v[124:127]
	v_mfma_f32_16x16x32_bf16 v[120:123], v[148:151], v[218:221], v[120:123]
	v_mfma_f32_16x16x32_bf16 v[112:115], v[156:159], v[218:221], v[112:115]
	v_mfma_f32_16x16x32_bf16 v[104:107], v[148:151], v[226:229], v[104:107]
	v_mfma_f32_16x16x32_bf16 v[96:99], v[156:159], v[226:229], v[96:99]
	v_mfma_f32_16x16x32_bf16 v[88:91], v[148:151], v[234:237], v[88:91]
	v_mfma_f32_16x16x32_bf16 v[80:83], v[156:159], v[234:237], v[80:83]
	v_mfma_f32_16x16x32_bf16 v[128:131], v[152:155], v[214:217], v[128:131]
	v_mfma_f32_16x16x32_bf16 v[124:127], v[160:163], v[214:217], v[124:127]
	v_mfma_f32_16x16x32_bf16 v[120:123], v[152:155], v[222:225], v[120:123]
	v_mfma_f32_16x16x32_bf16 v[112:115], v[160:163], v[222:225], v[112:115]
	v_mfma_f32_16x16x32_bf16 v[104:107], v[152:155], v[230:233], v[104:107]
	v_mfma_f32_16x16x32_bf16 v[96:99], v[160:163], v[230:233], v[96:99]
	v_mfma_f32_16x16x32_bf16 v[88:91], v[152:155], v[238:241], v[88:91]
	v_mfma_f32_16x16x32_bf16 v[80:83], v[160:163], v[238:241], v[80:83]
	v_mfma_f32_16x16x32_bf16 v[116:119], v[164:167], v[210:213], v[116:119]
	v_mfma_f32_16x16x32_bf16 v[108:111], v[202:205], v[210:213], v[108:111]
	v_mfma_f32_16x16x32_bf16 v[100:103], v[164:167], v[218:221], v[100:103]
	v_mfma_f32_16x16x32_bf16 v[92:95], v[202:205], v[218:221], v[92:95]
	v_mfma_f32_16x16x32_bf16 v[84:87], v[164:167], v[226:229], v[84:87]
	v_mfma_f32_16x16x32_bf16 v[76:79], v[202:205], v[226:229], v[76:79]
	v_mfma_f32_16x16x32_bf16 v[72:75], v[164:167], v[234:237], v[72:75]
	v_mfma_f32_16x16x32_bf16 v[68:71], v[202:205], v[234:237], v[68:71]
	v_mfma_f32_16x16x32_bf16 v[116:119], v[198:201], v[214:217], v[116:119]
	v_mfma_f32_16x16x32_bf16 v[108:111], v[206:209], v[214:217], v[108:111]
	v_mfma_f32_16x16x32_bf16 v[100:103], v[198:201], v[222:225], v[100:103]
	v_mfma_f32_16x16x32_bf16 v[92:95], v[206:209], v[222:225], v[92:95]
	v_mfma_f32_16x16x32_bf16 v[84:87], v[198:201], v[230:233], v[84:87]
	v_mfma_f32_16x16x32_bf16 v[76:79], v[206:209], v[230:233], v[76:79]
	v_mfma_f32_16x16x32_bf16 v[72:75], v[198:201], v[238:241], v[72:75]
	v_mfma_f32_16x16x32_bf16 v[68:71], v[206:209], v[238:241], v[68:71]
	s_setprio 0
	s_barrier
; #define PG8_STAGE(bufoff, gbase, voff) do { _Pragma("unroll") for (int _i = 0; _i < 2; ++_i) \
;         __builtin_amdgcn_global_load_lds((const unsigned*)((const char*)(gbase) + (voff)[_i]), (PG8_LAS unsigned*)(lds + (bufoff) + ldsw + _i * 8192), 16, 0, 0); } while (0)
; #define PG8_LDA(dst, b, h) do { _Pragma("unroll") for (int m = 0; m < 4; ++m) _Pragma("unroll") for (int k = 0; k < 2; ++k) dst[m][k] = *(const PG8_LAS bf16x8*)(lds + PG8_SA(b, h) + aoff + m * 2048 + k * 1024); } while (0)
; #define PG8_MMA(ai, bj, At, Bt) do { __builtin_amdgcn_s_setprio(1); _Pragma("unroll") for (int m = 0; m < 4; ++m) _Pragma("unroll") for (int n = 0; n < 2; ++n) _Pragma("unroll") for (int k = 0; k < 2; ++k) \
;         acc[ai][bj][m][n] = __builtin_amdgcn_mfma_f32_16x16x32_bf16(Bt[n][k], At[m][k], acc[ai][bj][m][n], 0, 0, 0); __builtin_amdgcn_s_setprio(0); } while (0)
; #define PG8_WAIT_V(n) asm volatile("s_waitcnt vmcnt(" #n ")" ::: "memory")
; #define PG8_WAIT_L(n) asm volatile("s_waitcnt lgkmcnt(" #n ")" ::: "memory")
; #define PG8_BAR __builtin_amdgcn_s_barrier()
; #define PG8_SCHED __builtin_amdgcn_sched_barrier(0)
; template <class Epi, class Sched, bool ALIGN_EPI = false, bool SP2 = false>
; __device__ __forceinline__ void gemm_phase(PG8_LAS unsigned char* lds, const Gemm g, const Sched& S, const Epi& E) {
;     ...
;         for (int t = 0; t < nt; t += 2) {
;     ...
;             PG8_LDA(At, 1, 1); PG8_STAGE(PG8_SB(1, 0), b3, voffB); PG8_STAGE(PG8_SB(1, 1), b3 + hstep, voffB); PG8_STAGE(PG8_SA(1, 0), a3, voffA);
;             PG8_WAIT_V(8); PG8_WAIT_L(0); PG8_BAR; PG8_MMA(1, 0, At, B0); PG8_MMA(1, 1, At, B1); PG8_BAR; PG8_SCHED;
	s_add_i32 s34, s68, s42
	v_lshl_add_u64 v[144:145], v[144:145], 0, s[84:85]
	s_mov_b32 m0, s34
	ds_read_b128 v[210:213], v147 offset:49152
	ds_read_b128 v[214:217], v147 offset:50176
	ds_read_b128 v[218:221], v147 offset:51200
	ds_read_b128 v[222:225], v147 offset:52224
	ds_read_b128 v[226:229], v147 offset:53248
	ds_read_b128 v[230:233], v147 offset:54272
	ds_read_b128 v[234:237], v147 offset:55296
	ds_read_b128 v[238:241], v147 offset:56320
	global_load_lds_dwordx4 v[144:145], off
	v_lshl_add_u64 v[144:145], v[242:243], 0, s[84:85]
	s_add_i32 m0, s34, 0x2000
	s_add_i32 s34, s69, s42
	global_load_lds_dwordx4 v[144:145], off
	v_lshl_add_u64 v[144:145], v[248:249], 0, s[84:85]
	s_mov_b32 m0, s34
	s_nop 0
	global_load_lds_dwordx4 v[144:145], off
	v_lshl_add_u64 v[144:145], v[250:251], 0, s[84:85]
	s_add_i32 m0, s34, 0x2000
	s_nop 0
	global_load_lds_dwordx4 v[144:145], off
	v_lshl_add_u64 v[144:145], v[252:253], 0, s[84:85]
	s_mov_b32 m0, s54
	s_nop 0
	global_load_lds_dwordx4 v[144:145], off
	v_lshl_add_u64 v[144:145], v[194:195], 0, s[84:85]
	s_mov_b32 m0, s55
	s_nop 0
	global_load_lds_dwordx4 v[144:145], off
	s_waitcnt vmcnt(8)
	s_waitcnt lgkmcnt(0)
	s_barrier
	s_setprio 1
	s_waitcnt lgkmcnt(0)
	v_mfma_f32_16x16x32_bf16 v[64:67], v[148:151], v[210:213], v[64:67]
	v_mfma_f32_16x16x32_bf16 v[60:63], v[156:159], v[210:213], v[60:63]
	v_mfma_f32_16x16x32_bf16 v[56:59], v[148:151], v[218:221], v[56:59]
	v_mfma_f32_16x16x32_bf16 v[48:51], v[156:159], v[218:221], v[48:51]
	v_mfma_f32_16x16x32_bf16 v[40:43], v[148:151], v[226:229], v[40:43]
	v_mfma_f32_16x16x32_bf16 v[32:35], v[156:159], v[226:229], v[32:35]
	v_mfma_f32_16x16x32_bf16 v[24:27], v[148:151], v[234:237], v[24:27]
	v_mfma_f32_16x16x32_bf16 v[16:19], v[156:159], v[234:237], v[16:19]
	v_mfma_f32_16x16x32_bf16 v[64:67], v[152:155], v[214:217], v[64:67]
	v_mfma_f32_16x16x32_bf16 v[60:63], v[160:163], v[214:217], v[60:63]
	v_mfma_f32_16x16x32_bf16 v[56:59], v[152:155], v[222:225], v[56:59]
	v_mfma_f32_16x16x32_bf16 v[48:51], v[160:163], v[222:225], v[48:51]
	v_mfma_f32_16x16x32_bf16 v[40:43], v[152:155], v[230:233], v[40:43]
	v_mfma_f32_16x16x32_bf16 v[32:35], v[160:163], v[230:233], v[32:35]
	v_mfma_f32_16x16x32_bf16 v[24:27], v[152:155], v[238:241], v[24:27]
	v_mfma_f32_16x16x32_bf16 v[16:19], v[160:163], v[238:241], v[16:19]
	v_mfma_f32_16x16x32_bf16 v[52:55], v[164:167], v[210:213], v[52:55]
	v_mfma_f32_16x16x32_bf16 v[44:47], v[202:205], v[210:213], v[44:47]
	v_mfma_f32_16x16x32_bf16 v[36:39], v[164:167], v[218:221], v[36:39]
	v_mfma_f32_16x16x32_bf16 v[28:31], v[202:205], v[218:221], v[28:31]
	v_mfma_f32_16x16x32_bf16 v[20:23], v[164:167], v[226:229], v[20:23]
	v_mfma_f32_16x16x32_bf16 v[12:15], v[202:205], v[226:229], v[12:15]
	v_mfma_f32_16x16x32_bf16 v[8:11], v[164:167], v[234:237], v[8:11]
	v_mfma_f32_16x16x32_bf16 v[4:7], v[202:205], v[234:237], v[4:7]
	v_mfma_f32_16x16x32_bf16 v[52:55], v[198:201], v[214:217], v[52:55]
	v_mfma_f32_16x16x32_bf16 v[44:47], v[206:209], v[214:217], v[44:47]
	v_mfma_f32_16x16x32_bf16 v[36:39], v[198:201], v[222:225], v[36:39]
	v_mfma_f32_16x16x32_bf16 v[28:31], v[206:209], v[222:225], v[28:31]
	v_mfma_f32_16x16x32_bf16 v[20:23], v[198:201], v[230:233], v[20:23]
	v_mfma_f32_16x16x32_bf16 v[12:15], v[206:209], v[230:233], v[12:15]
	v_mfma_f32_16x16x32_bf16 v[8:11], v[198:201], v[238:241], v[8:11]
	v_mfma_f32_16x16x32_bf16 v[4:7], v[206:209], v[238:241], v[4:7]
	s_setprio 0
	s_barrier
	s_add_u32 s30, s30, 0x100
	s_addc_u32 s31, s31, 0
	s_add_u32 s65, s65, 0x100
	s_addc_u32 s66, s66, 0
	s_cmp_ge_u32 s67, s53
	s_mov_b32 s34, s67
	s_cbranch_scc0 .LBB0_313
	s_and_b64 vcc, exec, s[26:27]
	s_cbranch_vccz .LBB0_316
	s_barrier

; #define PG8_STAGE(bufoff, gbase, voff) do { _Pragma("unroll") for (int _i = 0; _i < 2; ++_i) \
;         __builtin_amdgcn_global_load_lds((const unsigned*)((const char*)(gbase) + (voff)[_i]), (PG8_LAS unsigned*)(lds + (bufoff) + ldsw + _i * 8192), 16, 0, 0); } while (0)
; #define PG8_LDA(dst, b, h) do { _Pragma("unroll") for (int m = 0; m < 4; ++m) _Pragma("unroll") for (int k = 0; k < 2; ++k) dst[m][k] = *(const PG8_LAS bf16x8*)(lds + PG8_SA(b, h) + aoff + m * 2048 + k * 1024); } while (0)
; #define PG8_LDB(dst, b, h) do { _Pragma("unroll") for (int n = 0; n < 2; ++n) _Pragma("unroll") for (int k = 0; k < 2; ++k) dst[n][k] = *(const PG8_LAS bf16x8*)(lds + PG8_SB(b, h) + boff + n * 2048 + k * 1024); } while (0)
; #define PG8_MMA(ai, bj, At, Bt) do { __builtin_amdgcn_s_setprio(1); _Pragma("unroll") for (int m = 0; m < 4; ++m) _Pragma("unroll") for (int n = 0; n < 2; ++n) _Pragma("unroll") for (int k = 0; k < 2; ++k) \
;         acc[ai][bj][m][n] = __builtin_amdgcn_mfma_f32_16x16x32_bf16(Bt[n][k], At[m][k], acc[ai][bj][m][n], 0, 0, 0); __builtin_amdgcn_s_setprio(0); } while (0)
; #define PG8_WAIT_V(n) asm volatile("s_waitcnt vmcnt(" #n ")" ::: "memory")
; #define PG8_WAIT_L(n) asm volatile("s_waitcnt lgkmcnt(" #n ")" ::: "memory")
; #define PG8_BAR __builtin_amdgcn_s_barrier()
; #define PG8_SCHED __builtin_amdgcn_sched_barrier(0)
; template <class Epi, class Sched, bool ALIGN_EPI = false, bool SP2 = false>
; __device__ __forceinline__ void gemm_phase(PG8_LAS unsigned char* lds, const Gemm g, const Sched& S, const Epi& E) {
;     ...
;         for (int t = 0; t < nt; t += 2) {
;             const bool last = (t == nt - 2);
;             const char* a1 = cA + (size_t)(t + 1) * kstep;
;             const char* a2 = last ? nA : cA + (size_t)(t + 2) * kstep; const char* b2 = last ? nB : cB + (size_t)(t + 2) * kstep;
;             const char* a3 = a2 + kstep; const char* b3 = b2 + kstep;
;             if (last && has_next) S.a_ready(nxt);
;             if constexpr (SP2) {
;             PG8_LDB(B0, 0, 0); PG8_LDB(B1, 0, 1); PG8_SCHED; PG8_LDA(At, 0, 0); PG8_STAGE(PG8_SA(1, 1), a1 + hstep, voffA);
;             PG8_WAIT_V(8); PG8_WAIT_L(0); PG8_BAR; PG8_MMA(0, 0, At, B0); PG8_MMA(0, 1, At, B1); PG8_BAR; PG8_SCHED;
;             PG8_LDA(At, 0, 1); PG8_STAGE(PG8_SB(0, 0), b2, voffB); PG8_STAGE(PG8_SB(0, 1), b2 + hstep, voffB); PG8_STAGE(PG8_SA(0, 0), a2, voffA);
.LBB0_332:
	s_add_i32 s45, s18, 2
	s_add_u32 s16, s12, 0x100
	s_addc_u32 s17, s13, 0
	s_cmp_lg_u32 s44, s18
	s_cselect_b32 s46, s16, 0
	s_cselect_b32 s47, s17, 0
	s_add_u32 s18, s8, s46
	s_addc_u32 s19, s9, s47
	s_add_u32 s46, s6, s46
	s_addc_u32 s47, s7, s47
	s_add_i32 s48, 0, 0x14000
	v_add_u32_e32 v158, s74, v144
	v_add_u32_e32 v166, s48, v144
	ds_read_b128 v[146:149], v158
	ds_read_b128 v[150:153], v158 offset:1024
	ds_read_b128 v[154:157], v158 offset:2048
	ds_read_b128 v[158:161], v158 offset:3072
	ds_read_b128 v[162:165], v166
	ds_read_b128 v[198:201], v166 offset:1024
	ds_read_b128 v[202:205], v166 offset:2048
	ds_read_b128 v[206:209], v166 offset:3072
	v_lshl_add_u64 v[166:167], v[140:141], 0, s[12:13]
	s_add_i32 m0, s31, 0xc000
	ds_read_b128 v[210:213], v145
	ds_read_b128 v[214:217], v145 offset:1024
	ds_read_b128 v[218:221], v145 offset:2048
	ds_read_b128 v[222:225], v145 offset:3072
	ds_read_b128 v[226:229], v145 offset:4096
	ds_read_b128 v[230:233], v145 offset:5120
	ds_read_b128 v[234:237], v145 offset:6144
	ds_read_b128 v[238:241], v145 offset:7168
	global_load_lds_dwordx4 v[166:167], off
	v_lshl_add_u64 v[166:167], v[142:143], 0, s[12:13]
	s_add_i32 m0, s31, 0xe000
	s_nop 0
	global_load_lds_dwordx4 v[166:167], off
	s_waitcnt vmcnt(8)
	s_waitcnt lgkmcnt(0)
	s_barrier
	s_setprio 1
	s_waitcnt lgkmcnt(0)
	v_mfma_f32_16x16x32_bf16 v[128:131], v[146:149], v[210:213], v[128:131]
	v_mfma_f32_16x16x32_bf16 v[124:127], v[154:157], v[210:213], v[124:127]
	v_mfma_f32_16x16x32_bf16 v[112:115], v[146:149], v[218:221], v[112:115]
	v_mfma_f32_16x16x32_bf16 v[108:111], v[154:157], v[218:221], v[108:111]
	v_mfma_f32_16x16x32_bf16 v[96:99], v[146:149], v[226:229], v[96:99]
	v_mfma_f32_16x16x32_bf16 v[92:95], v[154:157], v[226:229], v[92:95]
	v_mfma_f32_16x16x32_bf16 v[80:83], v[146:149], v[234:237], v[80:83]
	v_mfma_f32_16x16x32_bf16 v[76:79], v[154:157], v[234:237], v[76:79]
	v_mfma_f32_16x16x32_bf16 v[128:131], v[150:153], v[214:217], v[128:131]
	v_mfma_f32_16x16x32_bf16 v[124:127], v[158:161], v[214:217], v[124:127]
	v_mfma_f32_16x16x32_bf16 v[112:115], v[150:153], v[222:225], v[112:115]
	v_mfma_f32_16x16x32_bf16 v[108:111], v[158:161], v[222:225], v[108:111]
	v_mfma_f32_16x16x32_bf16 v[96:99], v[150:153], v[230:233], v[96:99]
	v_mfma_f32_16x16x32_bf16 v[92:95], v[158:161], v[230:233], v[92:95]
	v_mfma_f32_16x16x32_bf16 v[80:83], v[150:153], v[238:241], v[80:83]
	v_mfma_f32_16x16x32_bf16 v[76:79], v[158:161], v[238:241], v[76:79]
	v_mfma_f32_16x16x32_bf16 v[120:123], v[162:165], v[210:213], v[120:123]
	v_mfma_f32_16x16x32_bf16 v[116:119], v[202:205], v[210:213], v[116:119]
	v_mfma_f32_16x16x32_bf16 v[104:107], v[162:165], v[218:221], v[104:107]
	v_mfma_f32_16x16x32_bf16 v[100:103], v[202:205], v[218:221], v[100:103]
	v_mfma_f32_16x16x32_bf16 v[88:91], v[162:165], v[226:229], v[88:91]
	v_mfma_f32_16x16x32_bf16 v[84:87], v[202:205], v[226:229], v[84:87]
	v_mfma_f32_16x16x32_bf16 v[72:75], v[162:165], v[234:237], v[72:75]
	v_mfma_f32_16x16x32_bf16 v[68:71], v[202:205], v[234:237], v[68:71]
	v_mfma_f32_16x16x32_bf16 v[120:123], v[198:201], v[214:217], v[120:123]
	v_mfma_f32_16x16x32_bf16 v[116:119], v[206:209], v[214:217], v[116:119]
	v_mfma_f32_16x16x32_bf16 v[104:107], v[198:201], v[222:225], v[104:107]
	v_mfma_f32_16x16x32_bf16 v[100:103], v[206:209], v[222:225], v[100:103]
	v_mfma_f32_16x16x32_bf16 v[88:91], v[198:201], v[230:233], v[88:91]
	v_mfma_f32_16x16x32_bf16 v[84:87], v[206:209], v[230:233], v[84:87]
	v_mfma_f32_16x16x32_bf16 v[72:75], v[198:201], v[238:241], v[72:75]
	v_mfma_f32_16x16x32_bf16 v[68:71], v[206:209], v[238:241], v[68:71]
	s_setprio 0
	s_barrier
	s_add_i32 s12, s74, s30
	v_lshl_add_u64 v[166:167], s[46:47], 0, v[2:3]
	s_mov_b32 m0, s12
	ds_read_b128 v[210:213], v145 offset:16384
	ds_read_b128 v[214:217], v145 offset:17408
	ds_read_b128 v[218:221], v145 offset:18432
	ds_read_b128 v[222:225], v145 offset:19456
	ds_read_b128 v[226:229], v145 offset:20480
	ds_read_b128 v[230:233], v145 offset:21504
	ds_read_b128 v[234:237], v145 offset:22528
	ds_read_b128 v[238:241], v145 offset:23552
	global_load_lds_dwordx4 v[166:167], off
	s_add_i32 m0, s12, 0x2000
	s_add_u32 s12, s46, s58
	v_lshl_add_u64 v[194:195], s[46:47], 0, v[138:139]
	s_addc_u32 s13, s47, 0
	s_add_i32 s46, s48, s30
	global_load_lds_dwordx4 v[194:195], off
	v_lshl_add_u64 v[196:197], s[12:13], 0, v[2:3]
	s_mov_b32 m0, s46
	v_lshl_add_u64 v[242:243], s[12:13], 0, v[138:139]
	global_load_lds_dwordx4 v[196:197], off
	s_add_i32 m0, s46, 0x2000
	v_lshl_add_u64 v[248:249], s[18:19], 0, v[0:1]
	global_load_lds_dwordx4 v[242:243], off
	s_mov_b32 m0, s31
	v_lshl_add_u64 v[250:251], s[18:19], 0, v[136:137]
	global_load_lds_dwordx4 v[248:249], off
	s_mov_b32 m0, s34
	s_nop 0
	global_load_lds_dwordx4 v[250:251], off
	s_waitcnt vmcnt(8)
	s_waitcnt lgkmcnt(0)
	s_barrier
; #define PG8_STAGE(bufoff, gbase, voff) do { _Pragma("unroll") for (int _i = 0; _i < 2; ++_i) \
;         __builtin_amdgcn_global_load_lds((const unsigned*)((const char*)(gbase) + (voff)[_i]), (PG8_LAS unsigned*)(lds + (bufoff) + ldsw + _i * 8192), 16, 0, 0); } while (0)
; #define PG8_LDA(dst, b, h) do { _Pragma("unroll") for (int m = 0; m < 4; ++m) _Pragma("unroll") for (int k = 0; k < 2; ++k) dst[m][k] = *(const PG8_LAS bf16x8*)(lds + PG8_SA(b, h) + aoff + m * 2048 + k * 1024); } while (0)
; #define PG8_LDB(dst, b, h) do { _Pragma("unroll") for (int n = 0; n < 2; ++n) _Pragma("unroll") for (int k = 0; k < 2; ++k) dst[n][k] = *(const PG8_LAS bf16x8*)(lds + PG8_SB(b, h) + boff + n * 2048 + k * 1024); } while (0)
; #define PG8_MMA(ai, bj, At, Bt) do { __builtin_amdgcn_s_setprio(1); _Pragma("unroll") for (int m = 0; m < 4; ++m) _Pragma("unroll") for (int n = 0; n < 2; ++n) _Pragma("unroll") for (int k = 0; k < 2; ++k) \
;         acc[ai][bj][m][n] = __builtin_amdgcn_mfma_f32_16x16x32_bf16(Bt[n][k], At[m][k], acc[ai][bj][m][n], 0, 0, 0); __builtin_amdgcn_s_setprio(0); } while (0)
; #define PG8_WAIT_V(n) asm volatile("s_waitcnt vmcnt(" #n ")" ::: "memory")
; #define PG8_WAIT_L(n) asm volatile("s_waitcnt lgkmcnt(" #n ")" ::: "memory")
; #define PG8_BAR __builtin_amdgcn_s_barrier()
; #define PG8_SCHED __builtin_amdgcn_sched_barrier(0)
; template <class Epi, class Sched, bool ALIGN_EPI = false, bool SP2 = false>
; __device__ __forceinline__ void gemm_phase(PG8_LAS unsigned char* lds, const Gemm g, const Sched& S, const Epi& E) {
;     ...
;             PG8_WAIT_V(8); PG8_WAIT_L(0); PG8_BAR; PG8_MMA(1, 0, At, B0); PG8_MMA(1, 1, At, B1); PG8_BAR; PG8_SCHED;
;             PG8_LDB(B0, 1, 0); PG8_LDB(B1, 1, 1); PG8_SCHED; PG8_LDA(At, 1, 0); PG8_STAGE(PG8_SA(0, 1), a2 + hstep, voffA);
;             PG8_WAIT_V(8); PG8_WAIT_L(0); PG8_BAR; PG8_MMA(0, 0, At, B0); PG8_MMA(0, 1, At, B1); PG8_BAR; PG8_SCHED;
	s_setprio 1
	s_waitcnt lgkmcnt(0)
	v_mfma_f32_16x16x32_bf16 v[64:67], v[146:149], v[210:213], v[64:67]
	v_mfma_f32_16x16x32_bf16 v[60:63], v[154:157], v[210:213], v[60:63]
	v_mfma_f32_16x16x32_bf16 v[48:51], v[146:149], v[218:221], v[48:51]
	v_mfma_f32_16x16x32_bf16 v[44:47], v[154:157], v[218:221], v[44:47]
	v_mfma_f32_16x16x32_bf16 v[32:35], v[146:149], v[226:229], v[32:35]
	v_mfma_f32_16x16x32_bf16 v[28:31], v[154:157], v[226:229], v[28:31]
	v_mfma_f32_16x16x32_bf16 v[16:19], v[146:149], v[234:237], v[16:19]
	v_mfma_f32_16x16x32_bf16 v[12:15], v[154:157], v[234:237], v[12:15]
	v_mfma_f32_16x16x32_bf16 v[64:67], v[150:153], v[214:217], v[64:67]
	v_mfma_f32_16x16x32_bf16 v[60:63], v[158:161], v[214:217], v[60:63]
	v_mfma_f32_16x16x32_bf16 v[48:51], v[150:153], v[222:225], v[48:51]
	v_mfma_f32_16x16x32_bf16 v[44:47], v[158:161], v[222:225], v[44:47]
	v_mfma_f32_16x16x32_bf16 v[32:35], v[150:153], v[230:233], v[32:35]
	v_mfma_f32_16x16x32_bf16 v[28:31], v[158:161], v[230:233], v[28:31]
	v_mfma_f32_16x16x32_bf16 v[16:19], v[150:153], v[238:241], v[16:19]
	v_mfma_f32_16x16x32_bf16 v[12:15], v[158:161], v[238:241], v[12:15]
	v_mfma_f32_16x16x32_bf16 v[56:59], v[162:165], v[210:213], v[56:59]
	v_mfma_f32_16x16x32_bf16 v[52:55], v[202:205], v[210:213], v[52:55]
	v_mfma_f32_16x16x32_bf16 v[40:43], v[162:165], v[218:221], v[40:43]
	v_mfma_f32_16x16x32_bf16 v[36:39], v[202:205], v[218:221], v[36:39]
	v_mfma_f32_16x16x32_bf16 v[24:27], v[162:165], v[226:229], v[24:27]
	v_mfma_f32_16x16x32_bf16 v[20:23], v[202:205], v[226:229], v[20:23]
	v_mfma_f32_16x16x32_bf16 v[8:11], v[162:165], v[234:237], v[8:11]
	v_mfma_f32_16x16x32_bf16 v[4:7], v[202:205], v[234:237], v[4:7]
	v_mfma_f32_16x16x32_bf16 v[56:59], v[198:201], v[214:217], v[56:59]
	v_mfma_f32_16x16x32_bf16 v[52:55], v[206:209], v[214:217], v[52:55]
	v_mfma_f32_16x16x32_bf16 v[40:43], v[198:201], v[222:225], v[40:43]
	v_mfma_f32_16x16x32_bf16 v[36:39], v[206:209], v[222:225], v[36:39]
	v_mfma_f32_16x16x32_bf16 v[24:27], v[198:201], v[230:233], v[24:27]
	v_mfma_f32_16x16x32_bf16 v[20:23], v[206:209], v[230:233], v[20:23]
	v_mfma_f32_16x16x32_bf16 v[8:11], v[198:201], v[238:241], v[8:11]
	v_mfma_f32_16x16x32_bf16 v[4:7], v[206:209], v[238:241], v[4:7]
	s_setprio 0
	s_barrier
	s_add_i32 s46, 0, 0x18000
	s_add_i32 s47, 0, 0x1c000
	v_add_u32_e32 v158, s46, v144
	v_add_u32_e32 v206, s47, v144
	ds_read_b128 v[146:149], v158
	ds_read_b128 v[150:153], v158 offset:1024
	ds_read_b128 v[154:157], v158 offset:2048
	ds_read_b128 v[158:161], v158 offset:3072
	ds_read_b128 v[162:165], v206
	ds_read_b128 v[198:201], v206 offset:1024
	ds_read_b128 v[202:205], v206 offset:2048
	ds_read_b128 v[206:209], v206 offset:3072
	s_add_u32 s12, s18, s58
	s_addc_u32 s13, s19, 0
	s_mov_b32 m0, s35
	v_lshl_add_u64 v[252:253], s[12:13], 0, v[0:1]
	ds_read_b128 v[210:213], v145 offset:32768
	ds_read_b128 v[214:217], v145 offset:33792
	ds_read_b128 v[218:221], v145 offset:34816
	ds_read_b128 v[222:225], v145 offset:35840
	ds_read_b128 v[226:229], v145 offset:36864
	ds_read_b128 v[230:233], v145 offset:37888
	ds_read_b128 v[234:237], v145 offset:38912
	ds_read_b128 v[238:241], v145 offset:39936
	global_load_lds_dwordx4 v[252:253], off
	v_lshl_add_u64 v[252:253], s[12:13], 0, v[136:137]
	s_mov_b32 m0, s40
	s_nop 0
	global_load_lds_dwordx4 v[252:253], off
	s_waitcnt vmcnt(8)
	s_waitcnt lgkmcnt(0)
	s_barrier
	s_setprio 1
	s_waitcnt lgkmcnt(0)
	v_mfma_f32_16x16x32_bf16 v[128:131], v[146:149], v[210:213], v[128:131]
	v_mfma_f32_16x16x32_bf16 v[124:127], v[154:157], v[210:213], v[124:127]
	v_mfma_f32_16x16x32_bf16 v[112:115], v[146:149], v[218:221], v[112:115]
	v_mfma_f32_16x16x32_bf16 v[108:111], v[154:157], v[218:221], v[108:111]
	v_mfma_f32_16x16x32_bf16 v[96:99], v[146:149], v[226:229], v[96:99]
	v_mfma_f32_16x16x32_bf16 v[92:95], v[154:157], v[226:229], v[92:95]
	v_mfma_f32_16x16x32_bf16 v[80:83], v[146:149], v[234:237], v[80:83]
	v_mfma_f32_16x16x32_bf16 v[76:79], v[154:157], v[234:237], v[76:79]
	v_mfma_f32_16x16x32_bf16 v[128:131], v[150:153], v[214:217], v[128:131]
	v_mfma_f32_16x16x32_bf16 v[124:127], v[158:161], v[214:217], v[124:127]
	v_mfma_f32_16x16x32_bf16 v[112:115], v[150:153], v[222:225], v[112:115]
	v_mfma_f32_16x16x32_bf16 v[108:111], v[158:161], v[222:225], v[108:111]
	v_mfma_f32_16x16x32_bf16 v[96:99], v[150:153], v[230:233], v[96:99]
	v_mfma_f32_16x16x32_bf16 v[92:95], v[158:161], v[230:233], v[92:95]
	v_mfma_f32_16x16x32_bf16 v[80:83], v[150:153], v[238:241], v[80:83]
	v_mfma_f32_16x16x32_bf16 v[76:79], v[158:161], v[238:241], v[76:79]
	v_mfma_f32_16x16x32_bf16 v[120:123], v[162:165], v[210:213], v[120:123]
	v_mfma_f32_16x16x32_bf16 v[116:119], v[202:205], v[210:213], v[116:119]
	v_mfma_f32_16x16x32_bf16 v[104:107], v[162:165], v[218:221], v[104:107]
	v_mfma_f32_16x16x32_bf16 v[100:103], v[202:205], v[218:221], v[100:103]
	v_mfma_f32_16x16x32_bf16 v[88:91], v[162:165], v[226:229], v[88:91]
	v_mfma_f32_16x16x32_bf16 v[84:87], v[202:205], v[226:229], v[84:87]
	v_mfma_f32_16x16x32_bf16 v[72:75], v[162:165], v[234:237], v[72:75]
	v_mfma_f32_16x16x32_bf16 v[68:71], v[202:205], v[234:237], v[68:71]
	v_mfma_f32_16x16x32_bf16 v[120:123], v[198:201], v[214:217], v[120:123]
	v_mfma_f32_16x16x32_bf16 v[116:119], v[206:209], v[214:217], v[116:119]
	v_mfma_f32_16x16x32_bf16 v[104:107], v[198:201], v[222:225], v[104:107]
	v_mfma_f32_16x16x32_bf16 v[100:103], v[206:209], v[222:225], v[100:103]
	v_mfma_f32_16x16x32_bf16 v[88:91], v[198:201], v[230:233], v[88:91]
	v_mfma_f32_16x16x32_bf16 v[84:87], v[206:209], v[230:233], v[84:87]
	v_mfma_f32_16x16x32_bf16 v[72:75], v[198:201], v[238:241], v[72:75]
	v_mfma_f32_16x16x32_bf16 v[68:71], v[206:209], v[238:241], v[68:71]
	s_setprio 0
	s_barrier
; #define PG8_STAGE(bufoff, gbase, voff) do { _Pragma("unroll") for (int _i = 0; _i < 2; ++_i) \
;         __builtin_amdgcn_global_load_lds((const unsigned*)((const char*)(gbase) + (voff)[_i]), (PG8_LAS unsigned*)(lds + (bufoff) + ldsw + _i * 8192), 16, 0, 0); } while (0)
; #define PG8_LDA(dst, b, h) do { _Pragma("unroll") for (int m = 0; m < 4; ++m) _Pragma("unroll") for (int k = 0; k < 2; ++k) dst[m][k] = *(const PG8_LAS bf16x8*)(lds + PG8_SA(b, h) + aoff + m * 2048 + k * 1024); } while (0)
; #define PG8_MMA(ai, bj, At, Bt) do { __builtin_amdgcn_s_setprio(1); _Pragma("unroll") for (int m = 0; m < 4; ++m) _Pragma("unroll") for (int n = 0; n < 2; ++n) _Pragma("unroll") for (int k = 0; k < 2; ++k) \
;         acc[ai][bj][m][n] = __builtin_amdgcn_mfma_f32_16x16x32_bf16(Bt[n][k], At[m][k], acc[ai][bj][m][n], 0, 0, 0); __builtin_amdgcn_s_setprio(0); } while (0)
; #define PG8_WAIT_V(n) asm volatile("s_waitcnt vmcnt(" #n ")" ::: "memory")
; #define PG8_WAIT_L(n) asm volatile("s_waitcnt lgkmcnt(" #n ")" ::: "memory")
; #define PG8_BAR __builtin_amdgcn_s_barrier()
; #define PG8_SCHED __builtin_amdgcn_sched_barrier(0)
; __device__ __forceinline__ int bid_() { int t = blockIdx.x; asm volatile("" : "+s"(t)); return t; }
; template <class Epi, class Sched, bool ALIGN_EPI = false, bool SP2 = false>
; __device__ __forceinline__ void gemm_phase(PG8_LAS unsigned char* lds, const Gemm g, const Sched& S, const Epi& E) {
;     ...
;             PG8_LDA(At, 1, 1); PG8_STAGE(PG8_SB(1, 0), b3, voffB); PG8_STAGE(PG8_SB(1, 1), b3 + hstep, voffB); PG8_STAGE(PG8_SA(1, 0), a3, voffA);
;             PG8_WAIT_V(8); PG8_WAIT_L(0); PG8_BAR; PG8_MMA(1, 0, At, B0); PG8_MMA(1, 1, At, B1); PG8_BAR; PG8_SCHED;
; __global__ void __launch_bounds__(512, 2) mk_fwd(Params Pkarg) {
;     ...
;                     for (int c = bid_(); c < 256; c += (int)gridDim.x) {
	s_add_i32 s12, s46, s30
	v_lshl_add_u64 v[166:167], v[166:167], 0, s[84:85]
	s_mov_b32 m0, s12
	ds_read_b128 v[210:213], v145 offset:49152
	ds_read_b128 v[214:217], v145 offset:50176
	ds_read_b128 v[218:221], v145 offset:51200
	ds_read_b128 v[222:225], v145 offset:52224
	ds_read_b128 v[226:229], v145 offset:53248
	ds_read_b128 v[230:233], v145 offset:54272
	ds_read_b128 v[234:237], v145 offset:55296
	ds_read_b128 v[238:241], v145 offset:56320
	global_load_lds_dwordx4 v[166:167], off
	v_lshl_add_u64 v[166:167], v[194:195], 0, s[84:85]
	s_add_i32 m0, s12, 0x2000
	s_add_i32 s12, s47, s30
	global_load_lds_dwordx4 v[166:167], off
	v_lshl_add_u64 v[166:167], v[196:197], 0, s[84:85]
	s_mov_b32 m0, s12
	s_nop 0
	global_load_lds_dwordx4 v[166:167], off
	v_lshl_add_u64 v[166:167], v[242:243], 0, s[84:85]
	s_add_i32 m0, s12, 0x2000
	s_nop 0
	global_load_lds_dwordx4 v[166:167], off
	v_lshl_add_u64 v[166:167], v[248:249], 0, s[84:85]
	s_mov_b32 m0, s42
	s_nop 0
	global_load_lds_dwordx4 v[166:167], off
	v_lshl_add_u64 v[166:167], v[250:251], 0, s[84:85]
	s_mov_b32 m0, s43
	s_nop 0
	global_load_lds_dwordx4 v[166:167], off
	s_waitcnt vmcnt(8)
	s_waitcnt lgkmcnt(0)
	s_barrier
	s_setprio 1
	s_waitcnt lgkmcnt(0)
	v_mfma_f32_16x16x32_bf16 v[64:67], v[146:149], v[210:213], v[64:67]
	v_mfma_f32_16x16x32_bf16 v[60:63], v[154:157], v[210:213], v[60:63]
	v_mfma_f32_16x16x32_bf16 v[48:51], v[146:149], v[218:221], v[48:51]
	v_mfma_f32_16x16x32_bf16 v[44:47], v[154:157], v[218:221], v[44:47]
	v_mfma_f32_16x16x32_bf16 v[32:35], v[146:149], v[226:229], v[32:35]
	v_mfma_f32_16x16x32_bf16 v[28:31], v[154:157], v[226:229], v[28:31]
	v_mfma_f32_16x16x32_bf16 v[16:19], v[146:149], v[234:237], v[16:19]
	v_mfma_f32_16x16x32_bf16 v[12:15], v[154:157], v[234:237], v[12:15]
	v_mfma_f32_16x16x32_bf16 v[64:67], v[150:153], v[214:217], v[64:67]
	v_mfma_f32_16x16x32_bf16 v[60:63], v[158:161], v[214:217], v[60:63]
	v_mfma_f32_16x16x32_bf16 v[48:51], v[150:153], v[222:225], v[48:51]
	v_mfma_f32_16x16x32_bf16 v[44:47], v[158:161], v[222:225], v[44:47]
	v_mfma_f32_16x16x32_bf16 v[32:35], v[150:153], v[230:233], v[32:35]
	v_mfma_f32_16x16x32_bf16 v[28:31], v[158:161], v[230:233], v[28:31]
	v_mfma_f32_16x16x32_bf16 v[16:19], v[150:153], v[238:241], v[16:19]
	v_mfma_f32_16x16x32_bf16 v[12:15], v[158:161], v[238:241], v[12:15]
	v_mfma_f32_16x16x32_bf16 v[56:59], v[162:165], v[210:213], v[56:59]
	v_mfma_f32_16x16x32_bf16 v[52:55], v[202:205], v[210:213], v[52:55]
	v_mfma_f32_16x16x32_bf16 v[40:43], v[162:165], v[218:221], v[40:43]
	v_mfma_f32_16x16x32_bf16 v[36:39], v[202:205], v[218:221], v[36:39]
	v_mfma_f32_16x16x32_bf16 v[24:27], v[162:165], v[226:229], v[24:27]
	v_mfma_f32_16x16x32_bf16 v[20:23], v[202:205], v[226:229], v[20:23]
	v_mfma_f32_16x16x32_bf16 v[8:11], v[162:165], v[234:237], v[8:11]
	v_mfma_f32_16x16x32_bf16 v[4:7], v[202:205], v[234:237], v[4:7]
	v_mfma_f32_16x16x32_bf16 v[56:59], v[198:201], v[214:217], v[56:59]
	v_mfma_f32_16x16x32_bf16 v[52:55], v[206:209], v[214:217], v[52:55]
	v_mfma_f32_16x16x32_bf16 v[40:43], v[198:201], v[222:225], v[40:43]
	v_mfma_f32_16x16x32_bf16 v[36:39], v[206:209], v[222:225], v[36:39]
	v_mfma_f32_16x16x32_bf16 v[24:27], v[198:201], v[230:233], v[24:27]
	v_mfma_f32_16x16x32_bf16 v[20:23], v[206:209], v[230:233], v[20:23]
	v_mfma_f32_16x16x32_bf16 v[8:11], v[198:201], v[238:241], v[8:11]
	v_mfma_f32_16x16x32_bf16 v[4:7], v[206:209], v[238:241], v[4:7]
	s_setprio 0
	s_barrier
	s_cmp_ge_i32 s45, s41
	s_mov_b64 s[12:13], s[16:17]
	s_mov_b32 s18, s45
	s_cbranch_scc0 .LBB0_332
	s_cmpk_lt_u32 s28, 0x100
	s_cbranch_scc0 .LBB0_327
	s_branch .LBB0_335

; #define PG8_STAGE(bufoff, gbase, voff) do { _Pragma("unroll") for (int _i = 0; _i < 2; ++_i) \
;         __builtin_amdgcn_global_load_lds((const unsigned*)((const char*)(gbase) + (voff)[_i]), (PG8_LAS unsigned*)(lds + (bufoff) + ldsw + _i * 8192), 16, 0, 0); } while (0)
; #define PG8_LDA(dst, b, h) do { _Pragma("unroll") for (int m = 0; m < 4; ++m) _Pragma("unroll") for (int k = 0; k < 2; ++k) dst[m][k] = *(const PG8_LAS bf16x8*)(lds + PG8_SA(b, h) + aoff + m * 2048 + k * 1024); } while (0)
; #define PG8_LDB(dst, b, h) do { _Pragma("unroll") for (int n = 0; n < 2; ++n) _Pragma("unroll") for (int k = 0; k < 2; ++k) dst[n][k] = *(const PG8_LAS bf16x8*)(lds + PG8_SB(b, h) + boff + n * 2048 + k * 1024); } while (0)
; #define PG8_MMA(ai, bj, At, Bt) do { __builtin_amdgcn_s_setprio(1); _Pragma("unroll") for (int m = 0; m < 4; ++m) _Pragma("unroll") for (int n = 0; n < 2; ++n) _Pragma("unroll") for (int k = 0; k < 2; ++k) \
;         acc[ai][bj][m][n] = __builtin_amdgcn_mfma_f32_16x16x32_bf16(Bt[n][k], At[m][k], acc[ai][bj][m][n], 0, 0, 0); __builtin_amdgcn_s_setprio(0); } while (0)
; #define PG8_WAIT_V(n) asm volatile("s_waitcnt vmcnt(" #n ")" ::: "memory")
; #define PG8_WAIT_L(n) asm volatile("s_waitcnt lgkmcnt(" #n ")" ::: "memory")
; #define PG8_BAR __builtin_amdgcn_s_barrier()
; #define PG8_SCHED __builtin_amdgcn_sched_barrier(0)
; template <class Epi, class Sched, bool ALIGN_EPI = false, bool SP2 = false>
; __device__ __forceinline__ void gemm_phase(PG8_LAS unsigned char* lds, const Gemm g, const Sched& S, const Epi& E) {
;     ...
;         for (int t = 0; t < nt; t += 2) {
;             const bool last = (t == nt - 2);
;             const char* a1 = cA + (size_t)(t + 1) * kstep;
;             const char* a2 = last ? nA : cA + (size_t)(t + 2) * kstep; const char* b2 = last ? nB : cB + (size_t)(t + 2) * kstep;
;             const char* a3 = a2 + kstep; const char* b3 = b2 + kstep;
;             if (last && has_next) S.a_ready(nxt);
;             if constexpr (SP2) {
;             PG8_LDB(B0, 0, 0); PG8_LDB(B1, 0, 1); PG8_SCHED; PG8_LDA(At, 0, 0); PG8_STAGE(PG8_SA(1, 1), a1 + hstep, voffA);
;             PG8_WAIT_V(8); PG8_WAIT_L(0); PG8_BAR; PG8_MMA(0, 0, At, B0); PG8_MMA(0, 1, At, B1); PG8_BAR; PG8_SCHED;
;             PG8_LDA(At, 0, 1); PG8_STAGE(PG8_SB(0, 0), b2, voffB); PG8_STAGE(PG8_SB(0, 1), b2 + hstep, voffB); PG8_STAGE(PG8_SA(0, 0), a2, voffA);
.LBB0_353:
	s_add_u32 s22, s20, 0xfff80080
	s_addc_u32 s23, s21, -1
	s_cmp_eq_u32 s51, 28
	s_cselect_b32 s25, s13, s23
	s_cselect_b32 s24, s47, s22
	v_add_u32_e32 v144, s74, v135
	s_cselect_b32 s23, s11, s50
	s_cselect_b32 s22, s48, s49
	s_add_i32 s54, 0, 0x14000
	ds_read_b128 v[148:151], v144
	ds_read_b128 v[152:155], v144 offset:1024
	ds_read_b128 v[156:159], v144 offset:2048
	ds_read_b128 v[160:163], v144 offset:3072
	v_add_u32_e32 v144, s54, v135
	ds_read_b128 v[164:167], v144
	ds_read_b128 v[198:201], v144 offset:1024
	ds_read_b128 v[202:205], v144 offset:2048
	ds_read_b128 v[206:209], v144 offset:3072
	v_lshl_add_u64 v[144:145], s[20:21], 0, v[140:141]
	s_add_i32 m0, s38, 0xc000
	ds_read_b128 v[210:213], v147
	ds_read_b128 v[214:217], v147 offset:1024
	ds_read_b128 v[218:221], v147 offset:2048
	ds_read_b128 v[222:225], v147 offset:3072
	ds_read_b128 v[226:229], v147 offset:4096
	ds_read_b128 v[230:233], v147 offset:5120
	ds_read_b128 v[234:237], v147 offset:6144
	ds_read_b128 v[238:241], v147 offset:7168
	global_load_lds_dwordx4 v[144:145], off
	v_lshl_add_u64 v[144:145], s[20:21], 0, v[142:143]
	s_add_i32 m0, s38, 0xe000
	s_nop 0
	global_load_lds_dwordx4 v[144:145], off
	s_waitcnt vmcnt(8)
	s_waitcnt lgkmcnt(0)
	s_barrier
	s_setprio 1
	s_waitcnt lgkmcnt(0)
	v_mfma_f32_16x16x32_bf16 v[128:131], v[148:151], v[210:213], v[128:131]
	v_mfma_f32_16x16x32_bf16 v[120:123], v[156:159], v[210:213], v[120:123]
	v_mfma_f32_16x16x32_bf16 v[112:115], v[148:151], v[218:221], v[112:115]
	v_mfma_f32_16x16x32_bf16 v[104:107], v[156:159], v[218:221], v[104:107]
	v_mfma_f32_16x16x32_bf16 v[96:99], v[148:151], v[226:229], v[96:99]
	v_mfma_f32_16x16x32_bf16 v[88:91], v[156:159], v[226:229], v[88:91]
	v_mfma_f32_16x16x32_bf16 v[80:83], v[148:151], v[234:237], v[80:83]
	v_mfma_f32_16x16x32_bf16 v[72:75], v[156:159], v[234:237], v[72:75]
	v_mfma_f32_16x16x32_bf16 v[128:131], v[152:155], v[214:217], v[128:131]
	v_mfma_f32_16x16x32_bf16 v[120:123], v[160:163], v[214:217], v[120:123]
	v_mfma_f32_16x16x32_bf16 v[112:115], v[152:155], v[222:225], v[112:115]
	v_mfma_f32_16x16x32_bf16 v[104:107], v[160:163], v[222:225], v[104:107]
	v_mfma_f32_16x16x32_bf16 v[96:99], v[152:155], v[230:233], v[96:99]
	v_mfma_f32_16x16x32_bf16 v[88:91], v[160:163], v[230:233], v[88:91]
	v_mfma_f32_16x16x32_bf16 v[80:83], v[152:155], v[238:241], v[80:83]
	v_mfma_f32_16x16x32_bf16 v[72:75], v[160:163], v[238:241], v[72:75]
	v_mfma_f32_16x16x32_bf16 v[124:127], v[164:167], v[210:213], v[124:127]
	v_mfma_f32_16x16x32_bf16 v[116:119], v[202:205], v[210:213], v[116:119]
	v_mfma_f32_16x16x32_bf16 v[108:111], v[164:167], v[218:221], v[108:111]
	v_mfma_f32_16x16x32_bf16 v[100:103], v[202:205], v[218:221], v[100:103]
	v_mfma_f32_16x16x32_bf16 v[92:95], v[164:167], v[226:229], v[92:95]
	v_mfma_f32_16x16x32_bf16 v[84:87], v[202:205], v[226:229], v[84:87]
	v_mfma_f32_16x16x32_bf16 v[76:79], v[164:167], v[234:237], v[76:79]
	v_mfma_f32_16x16x32_bf16 v[68:71], v[202:205], v[234:237], v[68:71]
	v_mfma_f32_16x16x32_bf16 v[124:127], v[198:201], v[214:217], v[124:127]
	v_mfma_f32_16x16x32_bf16 v[116:119], v[206:209], v[214:217], v[116:119]
	v_mfma_f32_16x16x32_bf16 v[108:111], v[198:201], v[222:225], v[108:111]
	v_mfma_f32_16x16x32_bf16 v[100:103], v[206:209], v[222:225], v[100:103]
	v_mfma_f32_16x16x32_bf16 v[92:95], v[198:201], v[230:233], v[92:95]
	v_mfma_f32_16x16x32_bf16 v[84:87], v[206:209], v[230:233], v[84:87]
	v_mfma_f32_16x16x32_bf16 v[76:79], v[198:201], v[238:241], v[76:79]
	v_mfma_f32_16x16x32_bf16 v[68:71], v[206:209], v[238:241], v[68:71]
	s_setprio 0
	s_barrier
	s_add_i32 s52, s74, s34
	v_lshl_add_u64 v[144:145], s[22:23], 0, v[2:3]
	s_mov_b32 m0, s52
	ds_read_b128 v[210:213], v147 offset:16384
	ds_read_b128 v[214:217], v147 offset:17408
	ds_read_b128 v[218:221], v147 offset:18432
	ds_read_b128 v[222:225], v147 offset:19456
	ds_read_b128 v[226:229], v147 offset:20480
	ds_read_b128 v[230:233], v147 offset:21504
	ds_read_b128 v[234:237], v147 offset:22528
	ds_read_b128 v[238:241], v147 offset:23552
	global_load_lds_dwordx4 v[144:145], off
	s_add_i32 m0, s52, 0x2000
	s_add_u32 s52, s22, 0x80000
	v_lshl_add_u64 v[242:243], s[22:23], 0, v[0:1]
	s_addc_u32 s53, s23, 0
	s_add_i32 s54, s54, s34
	global_load_lds_dwordx4 v[242:243], off
	v_lshl_add_u64 v[248:249], s[52:53], 0, v[2:3]
	s_mov_b32 m0, s54
	v_lshl_add_u64 v[250:251], s[24:25], 0, v[136:137]
	global_load_lds_dwordx4 v[248:249], off
	v_lshl_add_u64 v[248:249], s[52:53], 0, v[0:1]
	s_add_i32 m0, s54, 0x2000
	s_nop 0
	global_load_lds_dwordx4 v[248:249], off
	v_lshl_add_u64 v[248:249], s[24:25], 0, v[138:139]
	s_mov_b32 m0, s38
	s_nop 0
	global_load_lds_dwordx4 v[248:249], off
	s_mov_b32 m0, s39
	s_nop 0
	global_load_lds_dwordx4 v[250:251], off
	s_waitcnt vmcnt(8)
	s_waitcnt lgkmcnt(0)
	s_barrier
; #define PG8_STAGE(bufoff, gbase, voff) do { _Pragma("unroll") for (int _i = 0; _i < 2; ++_i) \
;         __builtin_amdgcn_global_load_lds((const unsigned*)((const char*)(gbase) + (voff)[_i]), (PG8_LAS unsigned*)(lds + (bufoff) + ldsw + _i * 8192), 16, 0, 0); } while (0)
; #define PG8_LDA(dst, b, h) do { _Pragma("unroll") for (int m = 0; m < 4; ++m) _Pragma("unroll") for (int k = 0; k < 2; ++k) dst[m][k] = *(const PG8_LAS bf16x8*)(lds + PG8_SA(b, h) + aoff + m * 2048 + k * 1024); } while (0)
; #define PG8_LDB(dst, b, h) do { _Pragma("unroll") for (int n = 0; n < 2; ++n) _Pragma("unroll") for (int k = 0; k < 2; ++k) dst[n][k] = *(const PG8_LAS bf16x8*)(lds + PG8_SB(b, h) + boff + n * 2048 + k * 1024); } while (0)
; #define PG8_MMA(ai, bj, At, Bt) do { __builtin_amdgcn_s_setprio(1); _Pragma("unroll") for (int m = 0; m < 4; ++m) _Pragma("unroll") for (int n = 0; n < 2; ++n) _Pragma("unroll") for (int k = 0; k < 2; ++k) \
;         acc[ai][bj][m][n] = __builtin_amdgcn_mfma_f32_16x16x32_bf16(Bt[n][k], At[m][k], acc[ai][bj][m][n], 0, 0, 0); __builtin_amdgcn_s_setprio(0); } while (0)
; #define PG8_WAIT_V(n) asm volatile("s_waitcnt vmcnt(" #n ")" ::: "memory")
; #define PG8_WAIT_L(n) asm volatile("s_waitcnt lgkmcnt(" #n ")" ::: "memory")
; #define PG8_BAR __builtin_amdgcn_s_barrier()
; #define PG8_SCHED __builtin_amdgcn_sched_barrier(0)
; template <class Epi, class Sched, bool ALIGN_EPI = false, bool SP2 = false>
; __device__ __forceinline__ void gemm_phase(PG8_LAS unsigned char* lds, const Gemm g, const Sched& S, const Epi& E) {
;     ...
;             PG8_WAIT_V(8); PG8_WAIT_L(0); PG8_BAR; PG8_MMA(1, 0, At, B0); PG8_MMA(1, 1, At, B1); PG8_BAR; PG8_SCHED;
;             PG8_LDB(B0, 1, 0); PG8_LDB(B1, 1, 1); PG8_SCHED; PG8_LDA(At, 1, 0); PG8_STAGE(PG8_SA(0, 1), a2 + hstep, voffA);
;             PG8_WAIT_V(8); PG8_WAIT_L(0); PG8_BAR; PG8_MMA(0, 0, At, B0); PG8_MMA(0, 1, At, B1); PG8_BAR; PG8_SCHED;
	s_setprio 1
	s_waitcnt lgkmcnt(0)
	v_mfma_f32_16x16x32_bf16 v[64:67], v[148:151], v[210:213], v[64:67]
	v_mfma_f32_16x16x32_bf16 v[56:59], v[156:159], v[210:213], v[56:59]
	v_mfma_f32_16x16x32_bf16 v[48:51], v[148:151], v[218:221], v[48:51]
	v_mfma_f32_16x16x32_bf16 v[40:43], v[156:159], v[218:221], v[40:43]
	v_mfma_f32_16x16x32_bf16 v[32:35], v[148:151], v[226:229], v[32:35]
	v_mfma_f32_16x16x32_bf16 v[24:27], v[156:159], v[226:229], v[24:27]
	v_mfma_f32_16x16x32_bf16 v[16:19], v[148:151], v[234:237], v[16:19]
	v_mfma_f32_16x16x32_bf16 v[8:11], v[156:159], v[234:237], v[8:11]
	v_mfma_f32_16x16x32_bf16 v[64:67], v[152:155], v[214:217], v[64:67]
	v_mfma_f32_16x16x32_bf16 v[56:59], v[160:163], v[214:217], v[56:59]
	v_mfma_f32_16x16x32_bf16 v[48:51], v[152:155], v[222:225], v[48:51]
	v_mfma_f32_16x16x32_bf16 v[40:43], v[160:163], v[222:225], v[40:43]
	v_mfma_f32_16x16x32_bf16 v[32:35], v[152:155], v[230:233], v[32:35]
	v_mfma_f32_16x16x32_bf16 v[24:27], v[160:163], v[230:233], v[24:27]
	v_mfma_f32_16x16x32_bf16 v[16:19], v[152:155], v[238:241], v[16:19]
	v_mfma_f32_16x16x32_bf16 v[8:11], v[160:163], v[238:241], v[8:11]
	v_mfma_f32_16x16x32_bf16 v[60:63], v[164:167], v[210:213], v[60:63]
	v_mfma_f32_16x16x32_bf16 v[52:55], v[202:205], v[210:213], v[52:55]
	v_mfma_f32_16x16x32_bf16 v[44:47], v[164:167], v[218:221], v[44:47]
	v_mfma_f32_16x16x32_bf16 v[36:39], v[202:205], v[218:221], v[36:39]
	v_mfma_f32_16x16x32_bf16 v[28:31], v[164:167], v[226:229], v[28:31]
	v_mfma_f32_16x16x32_bf16 v[20:23], v[202:205], v[226:229], v[20:23]
	v_mfma_f32_16x16x32_bf16 v[12:15], v[164:167], v[234:237], v[12:15]
	v_mfma_f32_16x16x32_bf16 v[4:7], v[202:205], v[234:237], v[4:7]
	v_mfma_f32_16x16x32_bf16 v[60:63], v[198:201], v[214:217], v[60:63]
	v_mfma_f32_16x16x32_bf16 v[52:55], v[206:209], v[214:217], v[52:55]
	v_mfma_f32_16x16x32_bf16 v[44:47], v[198:201], v[222:225], v[44:47]
	v_mfma_f32_16x16x32_bf16 v[36:39], v[206:209], v[222:225], v[36:39]
	v_mfma_f32_16x16x32_bf16 v[28:31], v[198:201], v[230:233], v[28:31]
	v_mfma_f32_16x16x32_bf16 v[20:23], v[206:209], v[230:233], v[20:23]
	v_mfma_f32_16x16x32_bf16 v[12:15], v[198:201], v[238:241], v[12:15]
	v_mfma_f32_16x16x32_bf16 v[4:7], v[206:209], v[238:241], v[4:7]
	s_setprio 0
	s_barrier
	s_add_i32 s52, 0, 0x18000
	s_add_i32 s53, 0, 0x1c000
	v_add_u32_e32 v160, s52, v135
	v_add_u32_e32 v194, s53, v135
	ds_read_b128 v[148:151], v160
	ds_read_b128 v[152:155], v160 offset:1024
	ds_read_b128 v[156:159], v160 offset:2048
	ds_read_b128 v[160:163], v160 offset:3072
	ds_read_b128 v[164:167], v194
	ds_read_b128 v[198:201], v194 offset:1024
	ds_read_b128 v[202:205], v194 offset:2048
	ds_read_b128 v[206:209], v194 offset:3072
	s_add_u32 s24, s24, 0x80000
	s_addc_u32 s25, s25, 0
	s_mov_b32 m0, s40
	v_lshl_add_u64 v[252:253], s[24:25], 0, v[138:139]
	ds_read_b128 v[210:213], v147 offset:32768
	ds_read_b128 v[214:217], v147 offset:33792
	ds_read_b128 v[218:221], v147 offset:34816
	ds_read_b128 v[222:225], v147 offset:35840
	ds_read_b128 v[226:229], v147 offset:36864
	ds_read_b128 v[230:233], v147 offset:37888
	ds_read_b128 v[234:237], v147 offset:38912
	ds_read_b128 v[238:241], v147 offset:39936
	global_load_lds_dwordx4 v[252:253], off
	v_lshl_add_u64 v[252:253], s[24:25], 0, v[136:137]
	s_mov_b32 m0, s41
	s_nop 0
	global_load_lds_dwordx4 v[252:253], off
	s_waitcnt vmcnt(8)
	s_waitcnt lgkmcnt(0)
	s_barrier
	s_setprio 1
	s_waitcnt lgkmcnt(0)
	v_mfma_f32_16x16x32_bf16 v[128:131], v[148:151], v[210:213], v[128:131]
	v_mfma_f32_16x16x32_bf16 v[120:123], v[156:159], v[210:213], v[120:123]
	v_mfma_f32_16x16x32_bf16 v[112:115], v[148:151], v[218:221], v[112:115]
	v_mfma_f32_16x16x32_bf16 v[104:107], v[156:159], v[218:221], v[104:107]
	v_mfma_f32_16x16x32_bf16 v[96:99], v[148:151], v[226:229], v[96:99]
	v_mfma_f32_16x16x32_bf16 v[88:91], v[156:159], v[226:229], v[88:91]
	v_mfma_f32_16x16x32_bf16 v[80:83], v[148:151], v[234:237], v[80:83]
	v_mfma_f32_16x16x32_bf16 v[72:75], v[156:159], v[234:237], v[72:75]
	v_mfma_f32_16x16x32_bf16 v[128:131], v[152:155], v[214:217], v[128:131]
	v_mfma_f32_16x16x32_bf16 v[120:123], v[160:163], v[214:217], v[120:123]
	v_mfma_f32_16x16x32_bf16 v[112:115], v[152:155], v[222:225], v[112:115]
	v_mfma_f32_16x16x32_bf16 v[104:107], v[160:163], v[222:225], v[104:107]
	v_mfma_f32_16x16x32_bf16 v[96:99], v[152:155], v[230:233], v[96:99]
	v_mfma_f32_16x16x32_bf16 v[88:91], v[160:163], v[230:233], v[88:91]
	v_mfma_f32_16x16x32_bf16 v[80:83], v[152:155], v[238:241], v[80:83]
	v_mfma_f32_16x16x32_bf16 v[72:75], v[160:163], v[238:241], v[72:75]
	v_mfma_f32_16x16x32_bf16 v[124:127], v[164:167], v[210:213], v[124:127]
	v_mfma_f32_16x16x32_bf16 v[116:119], v[202:205], v[210:213], v[116:119]
	v_mfma_f32_16x16x32_bf16 v[108:111], v[164:167], v[218:221], v[108:111]
	v_mfma_f32_16x16x32_bf16 v[100:103], v[202:205], v[218:221], v[100:103]
	v_mfma_f32_16x16x32_bf16 v[92:95], v[164:167], v[226:229], v[92:95]
	v_mfma_f32_16x16x32_bf16 v[84:87], v[202:205], v[226:229], v[84:87]
	v_mfma_f32_16x16x32_bf16 v[76:79], v[164:167], v[234:237], v[76:79]
	v_mfma_f32_16x16x32_bf16 v[68:71], v[202:205], v[234:237], v[68:71]
	v_mfma_f32_16x16x32_bf16 v[124:127], v[198:201], v[214:217], v[124:127]
	v_mfma_f32_16x16x32_bf16 v[116:119], v[206:209], v[214:217], v[116:119]
	v_mfma_f32_16x16x32_bf16 v[108:111], v[198:201], v[222:225], v[108:111]
	v_mfma_f32_16x16x32_bf16 v[100:103], v[206:209], v[222:225], v[100:103]
	v_mfma_f32_16x16x32_bf16 v[92:95], v[198:201], v[230:233], v[92:95]
	v_mfma_f32_16x16x32_bf16 v[84:87], v[206:209], v[230:233], v[84:87]
	v_mfma_f32_16x16x32_bf16 v[76:79], v[198:201], v[238:241], v[76:79]
	v_mfma_f32_16x16x32_bf16 v[68:71], v[206:209], v[238:241], v[68:71]
	s_setprio 0
	s_barrier
; #define PG8_STAGE(bufoff, gbase, voff) do { _Pragma("unroll") for (int _i = 0; _i < 2; ++_i) \
;         __builtin_amdgcn_global_load_lds((const unsigned*)((const char*)(gbase) + (voff)[_i]), (PG8_LAS unsigned*)(lds + (bufoff) + ldsw + _i * 8192), 16, 0, 0); } while (0)
; #define PG8_LDA(dst, b, h) do { _Pragma("unroll") for (int m = 0; m < 4; ++m) _Pragma("unroll") for (int k = 0; k < 2; ++k) dst[m][k] = *(const PG8_LAS bf16x8*)(lds + PG8_SA(b, h) + aoff + m * 2048 + k * 1024); } while (0)
; #define PG8_MMA(ai, bj, At, Bt) do { __builtin_amdgcn_s_setprio(1); _Pragma("unroll") for (int m = 0; m < 4; ++m) _Pragma("unroll") for (int n = 0; n < 2; ++n) _Pragma("unroll") for (int k = 0; k < 2; ++k) \
;         acc[ai][bj][m][n] = __builtin_amdgcn_mfma_f32_16x16x32_bf16(Bt[n][k], At[m][k], acc[ai][bj][m][n], 0, 0, 0); __builtin_amdgcn_s_setprio(0); } while (0)
; #define PG8_WAIT_V(n) asm volatile("s_waitcnt vmcnt(" #n ")" ::: "memory")
; #define PG8_WAIT_L(n) asm volatile("s_waitcnt lgkmcnt(" #n ")" ::: "memory")
; #define PG8_BAR __builtin_amdgcn_s_barrier()
; #define PG8_SCHED __builtin_amdgcn_sched_barrier(0)
; template <class Epi, class Sched, bool ALIGN_EPI = false, bool SP2 = false>
; __device__ __forceinline__ void gemm_phase(PG8_LAS unsigned char* lds, const Gemm g, const Sched& S, const Epi& E) {
;     ...
;         for (int t = 0; t < nt; t += 2) {
;             const bool last = (t == nt - 2);
;             const char* a1 = cA + (size_t)(t + 1) * kstep;
;             const char* a2 = last ? nA : cA + (size_t)(t + 2) * kstep; const char* b2 = last ? nB : cB + (size_t)(t + 2) * kstep;
;     ...
;             PG8_LDA(At, 1, 1); PG8_STAGE(PG8_SB(1, 0), b3, voffB); PG8_STAGE(PG8_SB(1, 1), b3 + hstep, voffB); PG8_STAGE(PG8_SA(1, 0), a3, voffA);
;             PG8_WAIT_V(8); PG8_WAIT_L(0); PG8_BAR; PG8_MMA(1, 0, At, B0); PG8_MMA(1, 1, At, B1); PG8_BAR; PG8_SCHED;
	s_add_i32 s24, s52, s34
	v_lshl_add_u64 v[144:145], v[144:145], 0, s[84:85]
	s_mov_b32 m0, s24
	ds_read_b128 v[210:213], v147 offset:49152
	ds_read_b128 v[214:217], v147 offset:50176
	ds_read_b128 v[218:221], v147 offset:51200
	ds_read_b128 v[222:225], v147 offset:52224
	ds_read_b128 v[226:229], v147 offset:53248
	ds_read_b128 v[230:233], v147 offset:54272
	ds_read_b128 v[234:237], v147 offset:55296
	ds_read_b128 v[238:241], v147 offset:56320
	global_load_lds_dwordx4 v[144:145], off
	s_add_i32 m0, s24, 0x2000
	s_add_u32 s22, s22, 0x80080
	v_lshl_add_u64 v[144:145], v[242:243], 0, s[84:85]
	s_addc_u32 s23, s23, 0
	s_add_i32 s24, s53, s34
	global_load_lds_dwordx4 v[144:145], off
	v_lshl_add_u64 v[144:145], s[22:23], 0, v[2:3]
	s_mov_b32 m0, s24
	s_nop 0
	global_load_lds_dwordx4 v[144:145], off
	v_lshl_add_u64 v[144:145], s[22:23], 0, v[0:1]
	s_add_i32 m0, s24, 0x2000
	s_nop 0
	global_load_lds_dwordx4 v[144:145], off
	v_lshl_add_u64 v[144:145], v[248:249], 0, s[84:85]
	s_mov_b32 m0, s43
	s_nop 0
	global_load_lds_dwordx4 v[144:145], off
	v_lshl_add_u64 v[144:145], v[250:251], 0, s[84:85]
	s_mov_b32 m0, s44
	s_nop 0
	global_load_lds_dwordx4 v[144:145], off
	s_waitcnt vmcnt(8)
	s_waitcnt lgkmcnt(0)
	s_barrier
	s_setprio 1
	s_waitcnt lgkmcnt(0)
	v_mfma_f32_16x16x32_bf16 v[64:67], v[148:151], v[210:213], v[64:67]
	v_mfma_f32_16x16x32_bf16 v[56:59], v[156:159], v[210:213], v[56:59]
	v_mfma_f32_16x16x32_bf16 v[48:51], v[148:151], v[218:221], v[48:51]
	v_mfma_f32_16x16x32_bf16 v[40:43], v[156:159], v[218:221], v[40:43]
	v_mfma_f32_16x16x32_bf16 v[32:35], v[148:151], v[226:229], v[32:35]
	v_mfma_f32_16x16x32_bf16 v[24:27], v[156:159], v[226:229], v[24:27]
	v_mfma_f32_16x16x32_bf16 v[16:19], v[148:151], v[234:237], v[16:19]
	v_mfma_f32_16x16x32_bf16 v[8:11], v[156:159], v[234:237], v[8:11]
	v_mfma_f32_16x16x32_bf16 v[64:67], v[152:155], v[214:217], v[64:67]
	v_mfma_f32_16x16x32_bf16 v[56:59], v[160:163], v[214:217], v[56:59]
	v_mfma_f32_16x16x32_bf16 v[48:51], v[152:155], v[222:225], v[48:51]
	v_mfma_f32_16x16x32_bf16 v[40:43], v[160:163], v[222:225], v[40:43]
	v_mfma_f32_16x16x32_bf16 v[32:35], v[152:155], v[230:233], v[32:35]
	v_mfma_f32_16x16x32_bf16 v[24:27], v[160:163], v[230:233], v[24:27]
	v_mfma_f32_16x16x32_bf16 v[16:19], v[152:155], v[238:241], v[16:19]
	v_mfma_f32_16x16x32_bf16 v[8:11], v[160:163], v[238:241], v[8:11]
	v_mfma_f32_16x16x32_bf16 v[60:63], v[164:167], v[210:213], v[60:63]
	v_mfma_f32_16x16x32_bf16 v[52:55], v[202:205], v[210:213], v[52:55]
	v_mfma_f32_16x16x32_bf16 v[44:47], v[164:167], v[218:221], v[44:47]
	v_mfma_f32_16x16x32_bf16 v[36:39], v[202:205], v[218:221], v[36:39]
	v_mfma_f32_16x16x32_bf16 v[28:31], v[164:167], v[226:229], v[28:31]
	v_mfma_f32_16x16x32_bf16 v[20:23], v[202:205], v[226:229], v[20:23]
	v_mfma_f32_16x16x32_bf16 v[12:15], v[164:167], v[234:237], v[12:15]
	v_mfma_f32_16x16x32_bf16 v[4:7], v[202:205], v[234:237], v[4:7]
	v_mfma_f32_16x16x32_bf16 v[60:63], v[198:201], v[214:217], v[60:63]
	v_mfma_f32_16x16x32_bf16 v[52:55], v[206:209], v[214:217], v[52:55]
	v_mfma_f32_16x16x32_bf16 v[44:47], v[198:201], v[222:225], v[44:47]
	v_mfma_f32_16x16x32_bf16 v[36:39], v[206:209], v[222:225], v[36:39]
	v_mfma_f32_16x16x32_bf16 v[28:31], v[198:201], v[230:233], v[28:31]
	v_mfma_f32_16x16x32_bf16 v[20:23], v[206:209], v[230:233], v[20:23]
	v_mfma_f32_16x16x32_bf16 v[12:15], v[198:201], v[238:241], v[12:15]
	v_mfma_f32_16x16x32_bf16 v[4:7], v[206:209], v[238:241], v[4:7]
	s_setprio 0
	s_barrier
	s_add_i32 s51, s51, 2
	s_add_u32 s20, s20, 0x100
	s_addc_u32 s21, s21, 0
	s_add_u32 s49, s49, 0x100
	s_addc_u32 s50, s50, 0
	s_cmp_gt_u32 s51, 29
	s_cbranch_scc0 .LBB0_353
	s_and_b64 vcc, exec, s[8:9]
	s_cbranch_vccz .LBB0_356
	s_barrier
